# grid barrier poll interval s_sleep 16
# speedup vs baseline: 1.0123x; 1.0047x over previous
; __global__ void __launch_bounds__(NTH, 2) mega_kernel(Params p) {
;     ...
;   phase0a(p, smem);
;   wait_mod(p);
;   phase1(p);
;   phase0b(p, smem);
;   grid.sync();
.Lgs1_poll:
	global_load_dword v2, v0, s[6:7] offset:128 sc1
	s_waitcnt vmcnt(0)
	v_cmp_gt_u32_e32 vcc, s8, v2
	s_cbranch_vccz .Lgs1_done
	s_sleep 16
	s_branch .Lgs1_poll
